# P1 epilogue stores back to default cache policy (no sc0 sc1), SGPR-base addressing kept
# speedup vs baseline: 1.0112x; 1.0112x over previous
; __device__ __forceinline__ unsigned cvt_pk_bf16(float lo, float hi) { unsigned r; asm volatile("v_cvt_pk_bf16_f32 %0, %1, %2" : "=v"(r) : "v"(lo), "v"(hi)); return r; }
;     __device__ __forceinline__ void operator()(const f32x4 (&acc)[2][2][4][2], const Unit& u, int wr, int wc, int fr, int fq) const {
;         const int row0 = u.pm * BM + wr * 64 + fr; int colt = u.pn * BM; const int sec = colt >> 10; colt &= 1023;
;         bf16_t* base = O + (size_t)sec * SEC; const int col0 = colt + wc * 32 + 8 * fq;
; #pragma unroll
;         for (int ai = 0; ai < 2; ++ai)
; #pragma unroll
;             for (int m = 0; m < 4; ++m) { bf16_t* rowp = base + (size_t)(row0 + ai * HALF + m * 16) * 1024 + col0;
; #pragma unroll
;                 for (int bj = 0; bj < 2; ++bj) { const f32x4 v0 = acc[ai][bj][m][0], v1 = acc[ai][bj][m][1];
;                     u32x4 w; w.x = cvt_pk_bf16(v0[0], v0[1]); w.y = cvt_pk_bf16(v0[2], v0[3]); w.z = cvt_pk_bf16(v1[0], v1[1]); w.w = cvt_pk_bf16(v1[2], v1[3]);
;                     *(u32x4*)(rowp + bj * HALF) = w; } }
.LBB0_64:
	s_ashr_i32 s54, s86, 2
	s_lshl_b32 s21, s86, 9
	s_ashr_i32 s55, s54, 31
	s_and_b32 s21, s21, 0x600
	s_lshl_b64 s[54:55], s[54:55], 26
	s_lshl_b32 s96, s46, 19
	s_add_u32 s54, s38, s54
	s_addc_u32 s55, s39, s55
	s_add_u32 s96, s96, s21
	s_add_u32 s96, s54, s96
	s_addc_u32 s97, s55, 0
	v_cvt_pk_bf16_f32 v124, v124, v125
	v_cvt_pk_bf16_f32 v125, v126, v127
	v_cvt_pk_bf16_f32 v126, v120, v121
	v_cvt_pk_bf16_f32 v127, v122, v123
	global_store_dwordx4 v230, v[124:127], s[96:97]
	v_cvt_pk_bf16_f32 v112, v112, v113
	v_cvt_pk_bf16_f32 v113, v114, v115
	v_cvt_pk_bf16_f32 v114, v104, v105
	v_cvt_pk_bf16_f32 v115, v106, v107
	global_store_dwordx4 v230, v[112:115], s[96:97] offset:256
	v_cvt_pk_bf16_f32 v104, v116, v117
	v_cvt_pk_bf16_f32 v105, v118, v119
	v_cvt_pk_bf16_f32 v106, v108, v109
	v_cvt_pk_bf16_f32 v107, v110, v111
	s_add_u32 s98, s96, 0x8000
	s_addc_u32 s99, s97, 0
	global_store_dwordx4 v230, v[104:107], s[98:99]
	v_cvt_pk_bf16_f32 v96, v96, v97
	v_cvt_pk_bf16_f32 v97, v98, v99
	v_cvt_pk_bf16_f32 v98, v88, v89
	v_cvt_pk_bf16_f32 v99, v90, v91
	global_store_dwordx4 v230, v[96:99], s[98:99] offset:256
	v_cvt_pk_bf16_f32 v88, v100, v101
	v_cvt_pk_bf16_f32 v89, v102, v103
	v_cvt_pk_bf16_f32 v90, v92, v93
	v_cvt_pk_bf16_f32 v91, v94, v95
	s_add_u32 s98, s96, 0x10000
	s_addc_u32 s99, s97, 0
	global_store_dwordx4 v230, v[88:91], s[98:99]
	v_cvt_pk_bf16_f32 v80, v80, v81
	v_cvt_pk_bf16_f32 v81, v82, v83
	v_cvt_pk_bf16_f32 v82, v72, v73
	v_cvt_pk_bf16_f32 v83, v74, v75
	global_store_dwordx4 v230, v[80:83], s[98:99] offset:256
	v_cvt_pk_bf16_f32 v72, v84, v85
	v_cvt_pk_bf16_f32 v73, v86, v87
	v_cvt_pk_bf16_f32 v74, v76, v77
	v_cvt_pk_bf16_f32 v75, v78, v79
	s_add_u32 s98, s96, 0x18000
	s_addc_u32 s99, s97, 0
	global_store_dwordx4 v230, v[72:75], s[98:99]
	v_cvt_pk_bf16_f32 v68, v68, v69
	v_cvt_pk_bf16_f32 v69, v70, v71
	v_cvt_pk_bf16_f32 v70, v64, v65
	v_cvt_pk_bf16_f32 v71, v66, v67
	global_store_dwordx4 v230, v[68:71], s[98:99] offset:256
	v_cvt_pk_bf16_f32 v60, v60, v61
	v_cvt_pk_bf16_f32 v61, v62, v63
	v_cvt_pk_bf16_f32 v62, v56, v57
	v_cvt_pk_bf16_f32 v63, v58, v59
	s_add_u32 s98, s96, 0x40000
	s_addc_u32 s99, s97, 0
	global_store_dwordx4 v230, v[60:63], s[98:99]
	v_cvt_pk_bf16_f32 v48, v48, v49
	v_cvt_pk_bf16_f32 v49, v50, v51
	v_cvt_pk_bf16_f32 v50, v40, v41
	v_cvt_pk_bf16_f32 v51, v42, v43
	global_store_dwordx4 v230, v[48:51], s[98:99] offset:256
	v_cvt_pk_bf16_f32 v40, v52, v53
	v_cvt_pk_bf16_f32 v41, v54, v55
	v_cvt_pk_bf16_f32 v42, v44, v45
	v_cvt_pk_bf16_f32 v43, v46, v47
	s_add_u32 s98, s96, 0x48000
	s_addc_u32 s99, s97, 0
	global_store_dwordx4 v230, v[40:43], s[98:99]
	v_cvt_pk_bf16_f32 v32, v32, v33
	v_cvt_pk_bf16_f32 v33, v34, v35
	v_cvt_pk_bf16_f32 v34, v24, v25
	v_cvt_pk_bf16_f32 v35, v26, v27
	global_store_dwordx4 v230, v[32:35], s[98:99] offset:256
	v_cvt_pk_bf16_f32 v24, v36, v37
	v_cvt_pk_bf16_f32 v25, v38, v39
	v_cvt_pk_bf16_f32 v26, v28, v29
	v_cvt_pk_bf16_f32 v27, v30, v31
	s_add_u32 s98, s96, 0x50000
	s_addc_u32 s99, s97, 0
	global_store_dwordx4 v230, v[24:27], s[98:99]
	v_cvt_pk_bf16_f32 v16, v16, v17
	v_cvt_pk_bf16_f32 v17, v18, v19
	v_cvt_pk_bf16_f32 v18, v8, v9
	v_cvt_pk_bf16_f32 v19, v10, v11
	global_store_dwordx4 v230, v[16:19], s[98:99] offset:256
	v_cvt_pk_bf16_f32 v8, v20, v21
	v_cvt_pk_bf16_f32 v9, v22, v23
	v_cvt_pk_bf16_f32 v10, v12, v13
	v_cvt_pk_bf16_f32 v11, v14, v15
	s_add_u32 s98, s96, 0x58000
	s_addc_u32 s99, s97, 0
	global_store_dwordx4 v230, v[8:11], s[98:99]
	v_cvt_pk_bf16_f32 v4, v4, v5
	v_cvt_pk_bf16_f32 v5, v6, v7
	v_cvt_pk_bf16_f32 v6, v0, v1
	v_cvt_pk_bf16_f32 v7, v2, v3
	global_store_dwordx4 v230, v[4:7], s[98:99] offset:256
	s_andn2_b64 vcc, exec, s[0:1]
	s_mov_b64 s[0:1], -1
	s_cbranch_vccnz .LBB0_57
	s_andn2_b64 vcc, exec, s[6:7]
	s_cbranch_vccnz .LBB0_56
	s_barrier
	s_branch .LBB0_56
